# 7.5: packed v_pk_add_f32 beside PV2 MFMAs replaced by scalar v_add_f32 pairs (18 sites)
# baseline (speedup 1.0000x reference)
.Lattn_dma_done_a:
	v_exp_f32_e32 v172, v128
	v_exp_f32_e32 v170, v129
	v_exp_f32_e32 v176, v130
	v_exp_f32_e32 v168, v131
	v_exp_f32_e32 v182, v132
	v_exp_f32_e32 v178, v133
	v_exp_f32_e32 v188, v134
	v_exp_f32_e32 v174, v135
	v_exp_f32_e32 v192, v136
	v_exp_f32_e32 v186, v137
	v_exp_f32_e32 v194, v138
	v_exp_f32_e32 v180, v139
	v_exp_f32_e32 v196, v140
	v_exp_f32_e32 v190, v141
	v_exp_f32_e32 v198, v142
	v_exp_f32_e32 v184, v143
	v_cvt_pk_bf16_f32 v144, v173, v169
	v_cvt_pk_bf16_f32 v145, v177, v171
	v_cvt_pk_bf16_f32 v146, v183, v175
	v_cvt_pk_bf16_f32 v147, v189, v179
	v_cvt_pk_bf16_f32 v148, v193, v181
	v_cvt_pk_bf16_f32 v149, v195, v187
	v_cvt_pk_bf16_f32 v150, v197, v185
	v_cvt_pk_bf16_f32 v151, v199, v191
	v_cvt_pk_bf16_f32 v128, v172, v170
	v_cvt_pk_bf16_f32 v129, v176, v168
	v_cvt_pk_bf16_f32 v130, v182, v178
	v_cvt_pk_bf16_f32 v131, v188, v174
	v_cvt_pk_bf16_f32 v132, v192, v186
	v_cvt_pk_bf16_f32 v133, v194, v180
	v_cvt_pk_bf16_f32 v134, v196, v190
	v_cvt_pk_bf16_f32 v135, v198, v184
	v_add3_u32 v160, s7, v162, v160
	v_xad_u32 v252, v163, 64, s7
	v_add_u32_e32 v203, s7, v203
	v_add_u32_e32 v205, s7, v206
	ds_read_b64_tr_b16 v[136:137], v160 offset:32768
	ds_read_b64_tr_b16 v[138:139], v160 offset:34816
	ds_read_b64_tr_b16 v[140:141], v160 offset:36864
	ds_read_b64_tr_b16 v[142:143], v160 offset:38912
	ds_read_b64_tr_b16 v[152:153], v252 offset:32768
	ds_read_b64_tr_b16 v[154:155], v252 offset:34816
	ds_read_b64_tr_b16 v[156:157], v252 offset:36864
	ds_read_b64_tr_b16 v[158:159], v252 offset:38912
	ds_read_b64_tr_b16 v[208:209], v203 offset:32768
	ds_read_b64_tr_b16 v[210:211], v203 offset:34816
	ds_read_b64_tr_b16 v[212:213], v203 offset:36864
	ds_read_b64_tr_b16 v[214:215], v203 offset:38912
	ds_read_b64_tr_b16 v[216:217], v205 offset:32768
	ds_read_b64_tr_b16 v[218:219], v205 offset:34816
	ds_read_b64_tr_b16 v[220:221], v205 offset:36864
	ds_read_b64_tr_b16 v[222:223], v205 offset:38912
	s_waitcnt lgkmcnt(14)
	v_mfma_f32_32x32x16_bf16 v[64:79], v[144:147], v[136:139], v[64:79]
	v_mfma_f32_32x32x16_bf16 v[0:15], v[128:131], v[136:139], v[0:15]
	s_waitcnt lgkmcnt(10)
	v_mfma_f32_32x32x16_bf16 v[80:95], v[144:147], v[152:155], v[80:95]
	v_mfma_f32_32x32x16_bf16 v[16:31], v[128:131], v[152:155], v[16:31]
	s_waitcnt lgkmcnt(6)
	v_mfma_f32_32x32x16_bf16 v[96:111], v[144:147], v[208:211], v[96:111]
	v_mfma_f32_32x32x16_bf16 v[32:47], v[128:131], v[208:211], v[32:47]
	s_waitcnt lgkmcnt(2)
	v_mfma_f32_32x32x16_bf16 v[112:127], v[144:147], v[216:219], v[112:127]
	v_mfma_f32_32x32x16_bf16 v[48:63], v[128:131], v[216:219], v[48:63]
	v_mfma_f32_32x32x16_bf16 v[64:79], v[148:151], v[140:143], v[64:79]
	v_mfma_f32_32x32x16_bf16 v[0:15], v[132:135], v[140:143], v[0:15]
	v_mfma_f32_32x32x16_bf16 v[80:95], v[148:151], v[156:159], v[80:95]
	v_mfma_f32_32x32x16_bf16 v[16:31], v[132:135], v[156:159], v[16:31]
	v_mfma_f32_32x32x16_bf16 v[96:111], v[148:151], v[212:215], v[96:111]
	v_mfma_f32_32x32x16_bf16 v[32:47], v[132:135], v[212:215], v[32:47]
	s_waitcnt lgkmcnt(0)
	v_mfma_f32_32x32x16_bf16 v[112:127], v[148:151], v[220:223], v[112:127]
	v_mfma_f32_32x32x16_bf16 v[48:63], v[132:135], v[220:223], v[48:63]
	ds_read_b128 v[128:131], v207 offset:4096
	ds_read_b128 v[132:135], v224
	ds_read_b128 v[136:139], v225 offset:4096
	ds_read_b128 v[140:143], v226
	s_waitcnt lgkmcnt(2)
	v_mfma_f32_32x32x16_bf16 v[144:159], v[128:131], v[132:135], 0
	ds_read_b128 v[128:131], v227 offset:4096
	ds_read_b128 v[132:135], v228
	s_waitcnt lgkmcnt(2)
	v_mfma_f32_32x32x16_bf16 v[144:159], v[136:139], v[140:143], v[144:159]
	ds_read_b128 v[136:139], v230 offset:4096
	ds_read_b128 v[140:143], v232
	s_waitcnt lgkmcnt(2)
	v_mfma_f32_32x32x16_bf16 v[144:159], v[128:131], v[132:135], v[144:159]
	ds_read_b128 v[128:131], v207 offset:12288
	ds_read_b128 v[132:135], v224 offset:4096
	s_waitcnt lgkmcnt(2)
	v_mfma_f32_32x32x16_bf16 v[144:159], v[136:139], v[140:143], v[144:159]
	ds_read_b128 v[208:211], v225 offset:12288
	ds_read_b128 v[212:215], v226 offset:4096
	s_waitcnt lgkmcnt(2)
	v_mfma_f32_32x32x16_bf16 v[128:143], v[128:131], v[132:135], 0
	s_nop 7
	v_exp_f32_e32 v229, v144
	v_exp_f32_e32 v145, v145
	v_exp_f32_e32 v231, v146
	v_exp_f32_e32 v147, v147
	ds_read_b128 v[216:219], v227 offset:12288
	ds_read_b128 v[220:223], v228 offset:4096
	s_waitcnt lgkmcnt(2)
	v_mfma_f32_32x32x16_bf16 v[128:143], v[208:211], v[212:215], v[128:143]
	v_exp_f32_e32 v233, v148
	v_exp_f32_e32 v235, v149
	v_exp_f32_e32 v237, v150
	v_exp_f32_e32 v239, v151
	ds_read_b128 v[148:151], v230 offset:12288
	ds_read_b128 v[208:211], v232 offset:4096
	s_waitcnt lgkmcnt(2)
	v_mfma_f32_32x32x16_bf16 v[128:143], v[216:219], v[220:223], v[128:143]
	v_exp_f32_e32 v241, v152
	v_exp_f32_e32 v243, v153
	v_exp_f32_e32 v245, v154
	v_exp_f32_e32 v247, v155
	s_waitcnt lgkmcnt(0)
	v_mfma_f32_32x32x16_bf16 v[128:143], v[148:151], v[208:211], v[128:143]
	v_exp_f32_e32 v249, v156
	v_exp_f32_e32 v251, v157
	v_exp_f32_e32 v207, v158
	v_exp_f32_e32 v163, v159
	s_nop 7
	v_exp_f32_e32 v228, v128
	v_exp_f32_e32 v146, v129
	v_exp_f32_e32 v230, v130
	v_exp_f32_e32 v144, v131
	v_exp_f32_e32 v232, v132
	v_exp_f32_e32 v238, v133
	v_exp_f32_e32 v236, v134
	v_exp_f32_e32 v234, v135
	v_exp_f32_e32 v240, v136
	v_exp_f32_e32 v246, v137
	v_exp_f32_e32 v244, v138
	v_exp_f32_e32 v242, v139
	v_exp_f32_e32 v248, v140
	v_exp_f32_e32 v162, v141
	v_exp_f32_e32 v206, v142
	v_exp_f32_e32 v250, v143
	v_cvt_pk_bf16_f32 v148, v229, v145
	v_cvt_pk_bf16_f32 v149, v231, v147
	v_cvt_pk_bf16_f32 v150, v233, v235
	v_cvt_pk_bf16_f32 v151, v237, v239
	v_cvt_pk_bf16_f32 v152, v241, v243
	v_cvt_pk_bf16_f32 v153, v245, v247
	v_cvt_pk_bf16_f32 v154, v249, v251
	v_cvt_pk_bf16_f32 v155, v207, v163
	v_cvt_pk_bf16_f32 v128, v228, v146
	v_cvt_pk_bf16_f32 v129, v230, v144
	v_cvt_pk_bf16_f32 v130, v232, v238
	v_cvt_pk_bf16_f32 v131, v236, v234
	v_cvt_pk_bf16_f32 v132, v240, v246
	v_cvt_pk_bf16_f32 v133, v244, v242
	v_cvt_pk_bf16_f32 v134, v248, v162
	v_cvt_pk_bf16_f32 v135, v206, v250
	ds_read_b64_tr_b16 v[136:137], v160 offset:40960
	ds_read_b64_tr_b16 v[138:139], v160 offset:43008
	ds_read_b64_tr_b16 v[140:141], v160 offset:45056
	ds_read_b64_tr_b16 v[142:143], v160 offset:47104
	ds_read_b64_tr_b16 v[156:157], v252 offset:40960
	ds_read_b64_tr_b16 v[158:159], v252 offset:43008
	ds_read_b64_tr_b16 v[208:209], v252 offset:45056
	ds_read_b64_tr_b16 v[210:211], v252 offset:47104
	ds_read_b64_tr_b16 v[212:213], v203 offset:40960
	ds_read_b64_tr_b16 v[214:215], v203 offset:43008
	ds_read_b64_tr_b16 v[216:217], v203 offset:45056
	ds_read_b64_tr_b16 v[218:219], v203 offset:47104
	ds_read_b64_tr_b16 v[220:221], v205 offset:40960
	ds_read_b64_tr_b16 v[222:223], v205 offset:43008
	ds_read_b64_tr_b16 v[224:225], v205 offset:45056
	ds_read_b64_tr_b16 v[226:227], v205 offset:47104
	s_waitcnt lgkmcnt(14)
	v_mfma_f32_32x32x16_bf16 v[64:79], v[148:151], v[136:139], v[64:79]
	v_mfma_f32_32x32x16_bf16 v[0:15], v[128:131], v[136:139], v[0:15]
	s_waitcnt lgkmcnt(10)
	v_mfma_f32_32x32x16_bf16 v[80:95], v[148:151], v[156:159], v[80:95]
	v_mfma_f32_32x32x16_bf16 v[16:31], v[128:131], v[156:159], v[16:31]
	s_waitcnt lgkmcnt(6)
	v_mfma_f32_32x32x16_bf16 v[96:111], v[148:151], v[212:215], v[96:111]
	v_mfma_f32_32x32x16_bf16 v[32:47], v[128:131], v[212:215], v[32:47]
	s_waitcnt lgkmcnt(2)
	v_mfma_f32_32x32x16_bf16 v[112:127], v[148:151], v[220:223], v[112:127]
	v_mfma_f32_32x32x16_bf16 v[48:63], v[128:131], v[220:223], v[48:63]
	v_add_f32_e64 v128, v172, v176
	v_add_f32_e64 v129, v173, v177
	v_add_f32_e64 v130, v168, v170
	v_add_f32_e64 v131, v169, v171
	v_add_f32_e64 v128, v128, 0
	v_add_f32_e64 v129, v129, 0
	v_add_f32_e32 v136, v182, v188
	v_add_f32_e32 v137, v183, v189
	v_add_f32_e64 v130, v130, 0
	v_add_f32_e64 v131, v131, 0
	v_add_f32_e32 v128, v136, v128
	v_add_f32_e32 v129, v137, v129
	v_add_f32_e32 v136, v174, v178
	v_add_f32_e32 v137, v175, v179
	v_add_f32_e32 v138, v232, v236
	v_add_f32_e32 v139, v233, v237
	v_add_f32_e32 v130, v136, v130
	v_add_f32_e32 v131, v137, v131
	v_add_f32_e32 v136, v192, v194
	v_add_f32_e32 v137, v193, v195
	v_mfma_f32_32x32x16_bf16 v[64:79], v[152:155], v[140:143], v[64:79]
	v_add_f32_e64 v128, v136, v128
	v_add_f32_e64 v129, v137, v129
	v_add_f32_e64 v136, v180, v186
	v_add_f32_e64 v137, v181, v187
	v_add_f32_e64 v130, v136, v130
	v_add_f32_e64 v131, v137, v131
	v_add_f32_e32 v136, v196, v198
	v_add_f32_e32 v137, v197, v199
	s_nop 0
	v_add_f32_e32 v128, v136, v128
	v_add_f32_e32 v129, v137, v129
	v_add_f32_e32 v136, v184, v190
	v_add_f32_e32 v137, v185, v191
	v_mfma_f32_32x32x16_bf16 v[0:15], v[132:135], v[140:143], v[0:15]
	v_add_f32_e64 v130, v136, v130
	v_add_f32_e64 v131, v137, v131
	v_add_f32_e64 v136, v144, v146
	v_add_f32_e64 v137, v145, v147
	v_add_f32_e64 v128, v128, v130
	v_add_f32_e64 v129, v129, v131
	v_add_f32_e32 v130, v228, v230
	v_add_f32_e32 v131, v229, v231
	v_add_f32_e64 v136, v136, 0
	v_add_f32_e64 v137, v137, 0
	v_add_f32_e64 v130, v130, 0
	v_add_f32_e64 v131, v131, 0
	v_add_f32_e32 v128, v166, v128
	v_add_f32_e32 v129, v167, v129
	v_mfma_f32_32x32x16_bf16 v[80:95], v[152:155], v[208:211], v[80:95]
	v_add_f32_e64 v130, v138, v130
	v_add_f32_e64 v131, v139, v131
	v_add_f32_e64 v138, v234, v238
	v_add_f32_e64 v139, v235, v239
	v_add_f32_e64 v136, v138, v136
	v_add_f32_e64 v137, v139, v137
	v_add_f32_e32 v138, v240, v244
	v_add_f32_e32 v139, v241, v245
	s_nop 0
	v_add_f32_e32 v130, v138, v130
	v_add_f32_e32 v131, v139, v131
	v_mfma_f32_32x32x16_bf16 v[16:31], v[132:135], v[208:211], v[16:31]
	v_add_f32_e64 v138, v242, v246
	v_add_f32_e64 v139, v243, v247
	v_add_f32_e64 v136, v138, v136
	v_add_f32_e64 v137, v139, v137
	v_add_f32_e64 v138, v248, v206
	v_add_f32_e64 v139, v249, v207
	v_add_f32_e32 v130, v138, v130
	v_add_f32_e32 v131, v139, v131
	v_add_f32_e32 v138, v250, v162
	v_add_f32_e32 v139, v251, v163
	v_mfma_f32_32x32x16_bf16 v[96:111], v[152:155], v[216:219], v[96:111]
	v_add_f32_e64 v136, v138, v136
	v_add_f32_e64 v137, v139, v137
	v_add_f32_e64 v130, v130, v136
	v_add_f32_e64 v131, v131, v137
	v_add_f32_e64 v166, v128, v130
	v_add_f32_e64 v167, v129, v131
	v_mfma_f32_32x32x16_bf16 v[32:47], v[132:135], v[216:219], v[32:47]
	s_waitcnt lgkmcnt(0)
	v_mfma_f32_32x32x16_bf16 v[112:127], v[152:155], v[224:227], v[112:127]
	v_mfma_f32_32x32x16_bf16 v[48:63], v[132:135], v[224:227], v[48:63]
	s_waitcnt vmcnt(0)
	s_waitcnt lgkmcnt(0)
	s_addk_i32 s5, 0x4000
	s_add_i32 s4, s4, 0x10000
	s_cmp_eq_u32 s4, 0x400000
	s_barrier
	s_cbranch_scc1 .LBB0_410
